# GEMM K-loops: global loads issued one per MFMA group (right before the matching ds_write) instead of as a burst after the barrier
# speedup vs baseline: 1.0154x; 1.0154x over previous
; template <int EPI>
; DI void gemm_phase(const P& p, int l, const u16* __restrict__ A, const u16* __restrict__ Bt, int mpx, char* lds) {
;     ...
;   const int tn = t + 1;
;   int m1 = 0, n1 = 0;
;   const bool has_next = tile_coords<EPI>(tn, mpx, m1, n1);
;   const u16* Agn = A + (size_t)m1 * 1024;
;   const u16* Bgn = Bt + (size_t)n1 * 1024;
;   f32x4 acc[8][4];
; #pragma unroll
;   for (int i = 0; i < 8; ++i)
; #pragma unroll
;     for (int j = 0; j < 4; ++j) acc[i][j] = zero4();
;   {
;   const int lane = tid & 63, w = tid >> 6, r = lane & 15, g = lane >> 4, wm = w >> 2, wn = w & 3;
;   __syncthreads();
;   GLOAD(Ag, Bg, 64)
;   __builtin_amdgcn_sched_barrier(0);
;   GCOMPUTE_KS(As0, Bs0, 0)
;   __builtin_amdgcn_sched_barrier(0);
;   GSTORE(As1, Bs1)
;   GLOAD(Ag, Bg, 128)
;   __builtin_amdgcn_sched_barrier(0);
;   GCOMPUTE_KS(As0, Bs0, 1)
.LBB0_69:
	v_lshl_add_u64 v[94:95], s[48:49], 0, v[196:197]
	v_add_co_u32_e32 v96, vcc, s33, v94
	v_lshl_add_u64 v[102:103], s[46:47], 0, v[196:197]
	s_nop 0
	v_addc_co_u32_e32 v97, vcc, 0, v95, vcc
	v_add_co_u32_e32 v98, vcc, s35, v94
	s_waitcnt lgkmcnt(0)
	s_nop 0
	v_addc_co_u32_e32 v99, vcc, 0, v95, vcc
	v_add_co_u32_e32 v100, vcc, s39, v94
	s_barrier
	s_nop 0
	v_addc_co_u32_e32 v101, vcc, 0, v95, vcc
	v_add_co_u32_e32 v104, vcc, s33, v102
	s_nop 1
	v_addc_co_u32_e32 v105, vcc, 0, v103, vcc
	v_add_co_u32_e32 v106, vcc, s35, v102
	global_load_dwordx4 v[2:5], v[94:95], off offset:128
	global_load_dwordx4 v[6:9], v[96:97], off offset:128
	v_addc_co_u32_e32 v107, vcc, 0, v103, vcc
	v_add_co_u32_e32 v110, vcc, s39, v102
	global_load_dwordx4 v[10:13], v[98:99], off offset:128
	global_load_dwordx4 v[14:17], v[100:101], off offset:128
	global_load_dwordx4 v[18:21], v[102:103], off offset:128
	global_load_dwordx4 v[22:25], v[104:105], off offset:128
	v_addc_co_u32_e32 v111, vcc, 0, v103, vcc
	global_load_dwordx4 v[26:29], v[106:107], off offset:128
	global_load_dwordx4 v[30:33], v[110:111], off offset:128
	s_add_i32 s56, s56, 1
	s_mul_i32 s2, s56, s57
	s_add_i32 s2, s2, s84
	s_cmp_ge_u32 s2, s25
	s_cselect_b64 s[40:41], -1, 0
	s_lshr_b32 s42, s2, 2
	s_add_i32 s42, s42, s51
	s_lshl_b32 s58, s42, 8
	s_lshl_b32 s42, s2, 8
	s_and_b32 s59, s42, 0x300
	s_lshl_b32 s42, s59, 11
	s_cmp_lt_u32 s2, s25
	s_cselect_b32 s2, s58, 0
	s_cselect_b32 s44, s42, 0
	s_lshl_b64 s[42:43], s[2:3], 11
	s_add_u32 s42, s16, s42
	s_mov_b32 s64, 1
	s_addc_u32 s43, s17, s43
	ds_read_b128 v[34:37], v227
	ds_read_b128 v[38:41], v207 offset:32768
	ds_read_b128 v[42:45], v207 offset:34816
	ds_read_b128 v[46:49], v227 offset:2048
	ds_read_b128 v[58:61], v207 offset:36864
	ds_read_b128 v[62:65], v207 offset:38912
	ds_read_b128 v[82:85], v227 offset:4096
	ds_read_b128 v[86:89], v227 offset:6144
	s_waitcnt lgkmcnt(6)
	v_mfma_f32_16x16x32_bf16 v[50:53], v[34:37], v[38:41], 0
	s_add_u32 s44, s26, s44
	s_addc_u32 s45, s27, 0
	s_waitcnt lgkmcnt(0)
	v_mfma_f32_16x16x32_bf16 v[126:129], v[86:89], v[38:41], 0
	v_mfma_f32_16x16x32_bf16 v[130:133], v[86:89], v[42:45], 0
	v_mfma_f32_16x16x32_bf16 v[134:137], v[86:89], v[58:61], 0
	v_mfma_f32_16x16x32_bf16 v[138:141], v[86:89], v[62:65], 0
	ds_read_b128 v[86:89], v227 offset:8192
	ds_read_b128 v[90:93], v227 offset:10240
	s_waitcnt lgkmcnt(1)
	v_mfma_f32_16x16x32_bf16 v[142:145], v[86:89], v[38:41], 0
	v_mfma_f32_16x16x32_bf16 v[146:149], v[86:89], v[42:45], 0
	v_mfma_f32_16x16x32_bf16 v[150:153], v[86:89], v[58:61], 0
	v_mfma_f32_16x16x32_bf16 v[154:157], v[86:89], v[62:65], 0
	s_waitcnt lgkmcnt(0)
	v_mfma_f32_16x16x32_bf16 v[158:161], v[90:93], v[38:41], 0
	v_mfma_f32_16x16x32_bf16 v[162:165], v[90:93], v[42:45], 0
	v_mfma_f32_16x16x32_bf16 v[166:169], v[90:93], v[58:61], 0
	v_mfma_f32_16x16x32_bf16 v[170:173], v[90:93], v[62:65], 0
	ds_read_b128 v[86:89], v227 offset:12288
	ds_read_b128 v[90:93], v227 offset:14336
	v_mfma_f32_16x16x32_bf16 v[54:57], v[34:37], v[42:45], 0
	v_mfma_f32_16x16x32_bf16 v[66:69], v[34:37], v[58:61], 0
	v_mfma_f32_16x16x32_bf16 v[34:37], v[34:37], v[62:65], 0
	v_mfma_f32_16x16x32_bf16 v[70:73], v[46:49], v[38:41], 0
	v_mfma_f32_16x16x32_bf16 v[74:77], v[46:49], v[42:45], 0
	v_mfma_f32_16x16x32_bf16 v[78:81], v[46:49], v[58:61], 0
	v_mfma_f32_16x16x32_bf16 v[46:49], v[46:49], v[62:65], 0
	v_mfma_f32_16x16x32_bf16 v[114:117], v[82:85], v[38:41], 0
	v_mfma_f32_16x16x32_bf16 v[118:121], v[82:85], v[42:45], 0
	v_mfma_f32_16x16x32_bf16 v[122:125], v[82:85], v[58:61], 0
	v_mfma_f32_16x16x32_bf16 v[82:85], v[82:85], v[62:65], 0
	s_waitcnt lgkmcnt(1)
	v_mfma_f32_16x16x32_bf16 v[174:177], v[86:89], v[38:41], 0
	v_mfma_f32_16x16x32_bf16 v[178:181], v[86:89], v[42:45], 0
	v_mfma_f32_16x16x32_bf16 v[182:185], v[86:89], v[58:61], 0
	v_mfma_f32_16x16x32_bf16 v[186:189], v[86:89], v[62:65], 0
	s_waitcnt lgkmcnt(0)
	v_mfma_f32_16x16x32_bf16 v[190:193], v[90:93], v[38:41], 0
	v_mfma_f32_16x16x32_bf16 v[212:215], v[90:93], v[42:45], 0
	v_mfma_f32_16x16x32_bf16 v[216:219], v[90:93], v[58:61], 0
	v_mfma_f32_16x16x32_bf16 v[220:223], v[90:93], v[62:65], 0
	s_waitcnt vmcnt(7)
	ds_write_b128 v199, v[2:5]
	s_waitcnt vmcnt(6)
	ds_write_b128 v200, v[6:9]
	s_waitcnt vmcnt(5)
	ds_write_b128 v201, v[10:13]
	s_waitcnt vmcnt(4)
	ds_write_b128 v202, v[14:17]
	s_waitcnt vmcnt(3)
	ds_write_b128 v203, v[18:21]
	s_waitcnt vmcnt(2)
	ds_write_b128 v204, v[22:25]
	s_waitcnt vmcnt(1)
	ds_write_b128 v205, v[26:29]
	s_waitcnt vmcnt(0)
	ds_write_b128 v206, v[30:33]
	global_load_dwordx4 v[18:21], v[94:95], off offset:256
	global_load_dwordx4 v[86:89], v[96:97], off offset:256
	global_load_dwordx4 v[90:93], v[98:99], off offset:256
	s_nop 0
	global_load_dwordx4 v[94:97], v[100:101], off offset:256
	s_nop 0
	global_load_dwordx4 v[98:101], v[102:103], off offset:256
	s_nop 0
	global_load_dwordx4 v[102:105], v[104:105], off offset:256
	s_nop 0
	global_load_dwordx4 v[106:109], v[106:107], off offset:256
	s_nop 0
	global_load_dwordx4 v[110:113], v[110:111], off offset:256
	ds_read_b128 v[2:5], v229
	ds_read_b128 v[234:237], v228 offset:32768
	ds_read_b128 v[238:241], v228 offset:34816
	ds_read_b128 v[242:245], v228 offset:36864
	ds_read_b128 v[246:249], v228 offset:38912
	s_waitcnt lgkmcnt(3)
	v_mfma_f32_16x16x32_bf16 v[6:9], v[2:5], v[234:237], v[50:53]
	s_waitcnt lgkmcnt(2)
	v_mfma_f32_16x16x32_bf16 v[10:13], v[2:5], v[238:241], v[54:57]
	s_waitcnt lgkmcnt(1)
	v_mfma_f32_16x16x32_bf16 v[14:17], v[2:5], v[242:245], v[66:69]
	s_waitcnt lgkmcnt(0)
	v_mfma_f32_16x16x32_bf16 v[22:25], v[2:5], v[246:249], v[34:37]
	ds_read_b128 v[2:5], v229 offset:2048
	s_waitcnt lgkmcnt(0)
; #define GCOMPUTE(AS, BS) GCOMPUTE_KS(AS, BS, 0) GCOMPUTE_KS(AS, BS, 1)
; template <int EPI>
; DI void gemm_phase(const P& p, int l, const u16* __restrict__ A, const u16* __restrict__ Bt, int mpx, char* lds) {
;     ...
;   GCOMPUTE_KS(As0, Bs0, 1)
;   __builtin_amdgcn_sched_barrier(0);
; #pragma unroll 1
;   for (int kk = 1; kk < 15; kk += 2) {
;     __syncthreads();
;     GSTORE(As0, Bs0)
;     GLOAD(Ag, Bg, (kk + 2) * 64)
;     __builtin_amdgcn_sched_barrier(0);
;     GCOMPUTE(As1, Bs1)
;     __builtin_amdgcn_sched_barrier(0);
;     __syncthreads();
;     GSTORE(As1, Bs1)
	v_mfma_f32_16x16x32_bf16 v[26:29], v[2:5], v[234:237], v[70:73]
	v_mfma_f32_16x16x32_bf16 v[30:33], v[2:5], v[238:241], v[74:77]
	v_mfma_f32_16x16x32_bf16 v[34:37], v[2:5], v[242:245], v[78:81]
	v_mfma_f32_16x16x32_bf16 v[38:41], v[2:5], v[246:249], v[46:49]
	ds_read_b128 v[2:5], v229 offset:4096
	s_waitcnt lgkmcnt(0)
	v_mfma_f32_16x16x32_bf16 v[42:45], v[2:5], v[234:237], v[114:117]
	v_mfma_f32_16x16x32_bf16 v[46:49], v[2:5], v[238:241], v[118:121]
	v_mfma_f32_16x16x32_bf16 v[50:53], v[2:5], v[242:245], v[122:125]
	v_mfma_f32_16x16x32_bf16 v[54:57], v[2:5], v[246:249], v[82:85]
	ds_read_b128 v[2:5], v229 offset:6144
	s_waitcnt lgkmcnt(0)
	v_mfma_f32_16x16x32_bf16 v[58:61], v[2:5], v[234:237], v[126:129]
	v_mfma_f32_16x16x32_bf16 v[62:65], v[2:5], v[238:241], v[130:133]
	v_mfma_f32_16x16x32_bf16 v[66:69], v[2:5], v[242:245], v[134:137]
	v_mfma_f32_16x16x32_bf16 v[70:73], v[2:5], v[246:249], v[138:141]
	ds_read_b128 v[2:5], v229 offset:8192
	s_waitcnt lgkmcnt(0)
	v_mfma_f32_16x16x32_bf16 v[74:77], v[2:5], v[234:237], v[142:145]
	v_mfma_f32_16x16x32_bf16 v[78:81], v[2:5], v[238:241], v[146:149]
	v_mfma_f32_16x16x32_bf16 v[82:85], v[2:5], v[242:245], v[150:153]
	v_mfma_f32_16x16x32_bf16 v[114:117], v[2:5], v[246:249], v[154:157]
	ds_read_b128 v[2:5], v229 offset:10240
	s_waitcnt lgkmcnt(0)
	v_mfma_f32_16x16x32_bf16 v[118:121], v[2:5], v[234:237], v[158:161]
	v_mfma_f32_16x16x32_bf16 v[122:125], v[2:5], v[238:241], v[162:165]
	v_mfma_f32_16x16x32_bf16 v[126:129], v[2:5], v[242:245], v[166:169]
	v_mfma_f32_16x16x32_bf16 v[130:133], v[2:5], v[246:249], v[170:173]
	ds_read_b128 v[2:5], v229 offset:12288
	s_waitcnt lgkmcnt(0)
	v_mfma_f32_16x16x32_bf16 v[134:137], v[2:5], v[234:237], v[174:177]
	v_mfma_f32_16x16x32_bf16 v[138:141], v[2:5], v[238:241], v[178:181]
	v_mfma_f32_16x16x32_bf16 v[142:145], v[2:5], v[242:245], v[182:185]
	v_mfma_f32_16x16x32_bf16 v[146:149], v[2:5], v[246:249], v[186:189]
	ds_read_b128 v[2:5], v229 offset:14336
	s_waitcnt lgkmcnt(0)
	v_mfma_f32_16x16x32_bf16 v[150:153], v[2:5], v[234:237], v[190:193]
	v_mfma_f32_16x16x32_bf16 v[154:157], v[2:5], v[238:241], v[212:215]
	v_mfma_f32_16x16x32_bf16 v[158:161], v[2:5], v[242:245], v[216:219]
	v_mfma_f32_16x16x32_bf16 v[2:5], v[2:5], v[246:249], v[220:223]
	s_movk_i32 s62, 0x100
	s_mov_b64 s[52:53], s[46:47]
	s_mov_b64 s[54:55], s[48:49]
	v_add_u32_e32 v208, s33, v196
	v_add_u32_e32 v209, s35, v196
	v_add_u32_e32 v210, s39, v196
	s_barrier
	ds_read_b128 v[212:215], v230
	ds_read_b128 v[216:219], v230 offset:2048
	ds_read_b128 v[220:223], v230 offset:4096
	ds_read_b128 v[234:237], v230 offset:6144
	ds_read_b128 v[238:241], v231
	ds_read_b128 v[242:245], v231 offset:2048
	ds_read_b128 v[246:249], v231 offset:4096
	ds_read_b128 v[250:253], v231 offset:6144
.LBB0_70:
	s_add_i32 s63, s64, 2
	s_waitcnt lgkmcnt(3)
	v_mfma_f32_16x16x32_bf16 v[6:9], v[238:241], v[212:215], v[6:9]
	v_mfma_f32_16x16x32_bf16 v[10:13], v[238:241], v[216:219], v[10:13]
	v_mfma_f32_16x16x32_bf16 v[14:17], v[238:241], v[220:223], v[14:17]
	v_mfma_f32_16x16x32_bf16 v[22:25], v[238:241], v[234:237], v[22:25]
	ds_read_b128 v[238:241], v231 offset:8192
	global_load_dwordx4 v[162:165], v196, s[54:55] offset:384
	s_waitcnt vmcnt(8)
	ds_write_b128 v198, v[18:21]
	s_waitcnt lgkmcnt(4)
	v_mfma_f32_16x16x32_bf16 v[26:29], v[242:245], v[212:215], v[26:29]
	v_mfma_f32_16x16x32_bf16 v[30:33], v[242:245], v[216:219], v[30:33]
	v_mfma_f32_16x16x32_bf16 v[34:37], v[242:245], v[220:223], v[34:37]
	v_mfma_f32_16x16x32_bf16 v[38:41], v[242:245], v[234:237], v[38:41]
	ds_read_b128 v[242:245], v231 offset:10240
	global_load_dwordx4 v[166:169], v208, s[54:55] offset:384
	s_waitcnt vmcnt(8)
	ds_write_b128 v198, v[86:89] offset:8192
	ds_read_b128 v[18:21], v232
	s_waitcnt lgkmcnt(6)
	v_mfma_f32_16x16x32_bf16 v[42:45], v[246:249], v[212:215], v[42:45]
	v_mfma_f32_16x16x32_bf16 v[46:49], v[246:249], v[216:219], v[46:49]
	v_mfma_f32_16x16x32_bf16 v[50:53], v[246:249], v[220:223], v[50:53]
	v_mfma_f32_16x16x32_bf16 v[54:57], v[246:249], v[234:237], v[54:57]
	ds_read_b128 v[246:249], v231 offset:12288
	global_load_dwordx4 v[170:173], v209, s[54:55] offset:384
	s_waitcnt vmcnt(8)
	ds_write_b128 v198, v[90:93] offset:16384
	ds_read_b128 v[86:89], v232 offset:2048
	s_waitcnt lgkmcnt(8)
	v_mfma_f32_16x16x32_bf16 v[58:61], v[250:253], v[212:215], v[58:61]
	v_mfma_f32_16x16x32_bf16 v[62:65], v[250:253], v[216:219], v[62:65]
	v_mfma_f32_16x16x32_bf16 v[66:69], v[250:253], v[220:223], v[66:69]
	v_mfma_f32_16x16x32_bf16 v[70:73], v[250:253], v[234:237], v[70:73]
	ds_read_b128 v[250:253], v231 offset:14336
	global_load_dwordx4 v[174:177], v210, s[54:55] offset:384
	s_waitcnt vmcnt(8)
	ds_write_b128 v198, v[94:97] offset:24576
	ds_read_b128 v[90:93], v232 offset:4096
	s_waitcnt lgkmcnt(10)
	v_mfma_f32_16x16x32_bf16 v[74:77], v[238:241], v[212:215], v[74:77]
	v_mfma_f32_16x16x32_bf16 v[78:81], v[238:241], v[216:219], v[78:81]
	v_mfma_f32_16x16x32_bf16 v[82:85], v[238:241], v[220:223], v[82:85]
	v_mfma_f32_16x16x32_bf16 v[114:117], v[238:241], v[234:237], v[114:117]
	ds_read_b128 v[238:241], v233
	global_load_dwordx4 v[178:181], v196, s[52:53] offset:384
	s_waitcnt vmcnt(8)
	ds_write_b128 v198, v[98:101] offset:32768
	ds_read_b128 v[94:97], v232 offset:6144
	s_waitcnt lgkmcnt(11)
	v_mfma_f32_16x16x32_bf16 v[118:121], v[242:245], v[212:215], v[118:121]
	v_mfma_f32_16x16x32_bf16 v[122:125], v[242:245], v[216:219], v[122:125]
	v_mfma_f32_16x16x32_bf16 v[126:129], v[242:245], v[220:223], v[126:129]
	v_mfma_f32_16x16x32_bf16 v[130:133], v[242:245], v[234:237], v[130:133]
	ds_read_b128 v[242:245], v233 offset:2048
	global_load_dwordx4 v[182:185], v208, s[52:53] offset:384
	s_waitcnt vmcnt(8)
; #define GCOMPUTE(AS, BS) GCOMPUTE_KS(AS, BS, 0) GCOMPUTE_KS(AS, BS, 1)
; template <int EPI>
; DI void gemm_phase(const P& p, int l, const u16* __restrict__ A, const u16* __restrict__ Bt, int mpx, char* lds) {
;     ...
;     __syncthreads();
;     GSTORE(As1, Bs1)
;     {
;       const bool in_tile = kk + 3 < 16;
;       const u16* pa = in_tile ? Ag : Agn;
;       const u16* pb = in_tile ? Bg : Bgn;
;       const int k0 = in_tile ? (kk + 3) * 64 : 0;
;       GLOAD(pa, pb, k0)
;     }
;     __builtin_amdgcn_sched_barrier(0);
;     GCOMPUTE(As0, Bs0)
	ds_write_b128 v198, v[102:105] offset:40960
	s_waitcnt lgkmcnt(10)
	v_mfma_f32_16x16x32_bf16 v[134:137], v[246:249], v[212:215], v[134:137]
	v_mfma_f32_16x16x32_bf16 v[138:141], v[246:249], v[216:219], v[138:141]
	v_mfma_f32_16x16x32_bf16 v[142:145], v[246:249], v[220:223], v[142:145]
	v_mfma_f32_16x16x32_bf16 v[146:149], v[246:249], v[234:237], v[146:149]
	ds_read_b128 v[246:249], v233 offset:4096
	global_load_dwordx4 v[186:189], v209, s[52:53] offset:384
	s_waitcnt vmcnt(8)
	ds_write_b128 v198, v[106:109] offset:49152
	s_waitcnt lgkmcnt(9)
	v_mfma_f32_16x16x32_bf16 v[150:153], v[250:253], v[212:215], v[150:153]
	v_mfma_f32_16x16x32_bf16 v[154:157], v[250:253], v[216:219], v[154:157]
	v_mfma_f32_16x16x32_bf16 v[158:161], v[250:253], v[220:223], v[158:161]
	v_mfma_f32_16x16x32_bf16 v[2:5], v[250:253], v[234:237], v[2:5]
	ds_read_b128 v[250:253], v233 offset:6144
	global_load_dwordx4 v[190:193], v210, s[52:53] offset:384
	s_waitcnt vmcnt(8)
	ds_write_b128 v198, v[110:113] offset:57344
	s_waitcnt lgkmcnt(6)
	v_mfma_f32_16x16x32_bf16 v[6:9], v[238:241], v[18:21], v[6:9]
	v_mfma_f32_16x16x32_bf16 v[10:13], v[238:241], v[86:89], v[10:13]
	v_mfma_f32_16x16x32_bf16 v[14:17], v[238:241], v[90:93], v[14:17]
	v_mfma_f32_16x16x32_bf16 v[22:25], v[238:241], v[94:97], v[22:25]
	ds_read_b128 v[238:241], v233 offset:8192
	s_waitcnt lgkmcnt(6)
	v_mfma_f32_16x16x32_bf16 v[26:29], v[242:245], v[18:21], v[26:29]
	v_mfma_f32_16x16x32_bf16 v[30:33], v[242:245], v[86:89], v[30:33]
	v_mfma_f32_16x16x32_bf16 v[34:37], v[242:245], v[90:93], v[34:37]
	v_mfma_f32_16x16x32_bf16 v[38:41], v[242:245], v[94:97], v[38:41]
	ds_read_b128 v[242:245], v233 offset:10240
	s_waitcnt lgkmcnt(5)
	v_mfma_f32_16x16x32_bf16 v[42:45], v[246:249], v[18:21], v[42:45]
	v_mfma_f32_16x16x32_bf16 v[46:49], v[246:249], v[86:89], v[46:49]
	v_mfma_f32_16x16x32_bf16 v[50:53], v[246:249], v[90:93], v[50:53]
	v_mfma_f32_16x16x32_bf16 v[54:57], v[246:249], v[94:97], v[54:57]
	ds_read_b128 v[246:249], v233 offset:12288
	s_waitcnt lgkmcnt(4)
	v_mfma_f32_16x16x32_bf16 v[58:61], v[250:253], v[18:21], v[58:61]
	v_mfma_f32_16x16x32_bf16 v[62:65], v[250:253], v[86:89], v[62:65]
	v_mfma_f32_16x16x32_bf16 v[66:69], v[250:253], v[90:93], v[66:69]
	v_mfma_f32_16x16x32_bf16 v[70:73], v[250:253], v[94:97], v[70:73]
	ds_read_b128 v[250:253], v233 offset:14336
	s_waitcnt lgkmcnt(3)
	v_mfma_f32_16x16x32_bf16 v[74:77], v[238:241], v[18:21], v[74:77]
	v_mfma_f32_16x16x32_bf16 v[78:81], v[238:241], v[86:89], v[78:81]
	v_mfma_f32_16x16x32_bf16 v[82:85], v[238:241], v[90:93], v[82:85]
	v_mfma_f32_16x16x32_bf16 v[114:117], v[238:241], v[94:97], v[114:117]
	s_waitcnt lgkmcnt(2)
	v_mfma_f32_16x16x32_bf16 v[118:121], v[242:245], v[18:21], v[118:121]
	v_mfma_f32_16x16x32_bf16 v[122:125], v[242:245], v[86:89], v[122:125]
	v_mfma_f32_16x16x32_bf16 v[126:129], v[242:245], v[90:93], v[126:129]
	v_mfma_f32_16x16x32_bf16 v[130:133], v[242:245], v[94:97], v[130:133]
	s_waitcnt lgkmcnt(0)
	s_cmp_lt_u32 s64, 13
	s_cselect_b64 s[66:67], -1, 0
	s_and_b64 s[66:67], s[66:67], exec
	s_cselect_b32 s2, s62, 0
	s_cselect_b32 s65, s49, s43
	s_cselect_b32 s68, s48, s42
	s_cselect_b32 s70, s47, s45
	s_cselect_b32 s71, s46, s44
	s_lshl_b64 s[66:67], s[2:3], 1
	s_add_u32 s68, s68, s66
	s_addc_u32 s69, s65, s67
	s_add_u32 s66, s71, s66
	s_addc_u32 s67, s70, s67
	s_barrier
	ds_read_b128 v[212:215], v207 offset:32768
	ds_read_b128 v[216:219], v207 offset:34816
	ds_read_b128 v[220:223], v207 offset:36864
	ds_read_b128 v[234:237], v207 offset:38912
	ds_read_b128 v[238:241], v227
	ds_read_b128 v[242:245], v227 offset:2048
	v_mfma_f32_16x16x32_bf16 v[134:137], v[246:249], v[18:21], v[134:137]
	v_mfma_f32_16x16x32_bf16 v[138:141], v[246:249], v[86:89], v[138:141]
	v_mfma_f32_16x16x32_bf16 v[142:145], v[246:249], v[90:93], v[142:145]
	v_mfma_f32_16x16x32_bf16 v[146:149], v[246:249], v[94:97], v[146:149]
	ds_read_b128 v[246:249], v227 offset:4096
	v_mfma_f32_16x16x32_bf16 v[150:153], v[250:253], v[18:21], v[150:153]
	v_mfma_f32_16x16x32_bf16 v[154:157], v[250:253], v[86:89], v[154:157]
	v_mfma_f32_16x16x32_bf16 v[158:161], v[250:253], v[90:93], v[158:161]
	v_mfma_f32_16x16x32_bf16 v[2:5], v[250:253], v[94:97], v[2:5]
	ds_read_b128 v[250:253], v227 offset:6144
	s_waitcnt lgkmcnt(3)
	v_mfma_f32_16x16x32_bf16 v[6:9], v[238:241], v[212:215], v[6:9]
	v_mfma_f32_16x16x32_bf16 v[10:13], v[238:241], v[216:219], v[10:13]
	v_mfma_f32_16x16x32_bf16 v[14:17], v[238:241], v[220:223], v[14:17]
	v_mfma_f32_16x16x32_bf16 v[22:25], v[238:241], v[234:237], v[22:25]
	ds_read_b128 v[238:241], v227 offset:8192
	global_load_dwordx4 v[18:21], v196, s[68:69]
	s_waitcnt vmcnt(8)
	ds_write_b128 v199, v[162:165]
	s_waitcnt lgkmcnt(4)
	v_mfma_f32_16x16x32_bf16 v[26:29], v[242:245], v[212:215], v[26:29]
	v_mfma_f32_16x16x32_bf16 v[30:33], v[242:245], v[216:219], v[30:33]
	v_mfma_f32_16x16x32_bf16 v[34:37], v[242:245], v[220:223], v[34:37]
	v_mfma_f32_16x16x32_bf16 v[38:41], v[242:245], v[234:237], v[38:41]
	ds_read_b128 v[242:245], v227 offset:10240
	global_load_dwordx4 v[86:89], v208, s[68:69]
	s_waitcnt vmcnt(8)
	ds_write_b128 v200, v[166:169]
	ds_read_b128 v[162:165], v228 offset:32768
	s_waitcnt lgkmcnt(6)
	v_mfma_f32_16x16x32_bf16 v[42:45], v[246:249], v[212:215], v[42:45]
	v_mfma_f32_16x16x32_bf16 v[46:49], v[246:249], v[216:219], v[46:49]
	v_mfma_f32_16x16x32_bf16 v[50:53], v[246:249], v[220:223], v[50:53]
	v_mfma_f32_16x16x32_bf16 v[54:57], v[246:249], v[234:237], v[54:57]
	ds_read_b128 v[246:249], v227 offset:12288
	global_load_dwordx4 v[90:93], v209, s[68:69]
	s_waitcnt vmcnt(8)
; #define GCOMPUTE(AS, BS) GCOMPUTE_KS(AS, BS, 0) GCOMPUTE_KS(AS, BS, 1)
; template <int EPI>
; DI void gemm_phase(const P& p, int l, const u16* __restrict__ A, const u16* __restrict__ Bt, int mpx, char* lds) {
;     ...
;   for (int kk = 1; kk < 15; kk += 2) {
;     __syncthreads();
;     GSTORE(As0, Bs0)
;     GLOAD(Ag, Bg, (kk + 2) * 64)
;     __builtin_amdgcn_sched_barrier(0);
;     GCOMPUTE(As1, Bs1)
;     __builtin_amdgcn_sched_barrier(0);
;     __syncthreads();
;     GSTORE(As1, Bs1)
;     {
;       const bool in_tile = kk + 3 < 16;
;       const u16* pa = in_tile ? Ag : Agn;
;       const u16* pb = in_tile ? Bg : Bgn;
;       const int k0 = in_tile ? (kk + 3) * 64 : 0;
;       GLOAD(pa, pb, k0)
;     }
;     __builtin_amdgcn_sched_barrier(0);
;     GCOMPUTE(As0, Bs0)
;     __builtin_amdgcn_sched_barrier(0);
;   }
	ds_write_b128 v201, v[170:173]
	ds_read_b128 v[166:169], v228 offset:34816
	s_waitcnt lgkmcnt(8)
	v_mfma_f32_16x16x32_bf16 v[58:61], v[250:253], v[212:215], v[58:61]
	v_mfma_f32_16x16x32_bf16 v[62:65], v[250:253], v[216:219], v[62:65]
	v_mfma_f32_16x16x32_bf16 v[66:69], v[250:253], v[220:223], v[66:69]
	v_mfma_f32_16x16x32_bf16 v[70:73], v[250:253], v[234:237], v[70:73]
	ds_read_b128 v[250:253], v227 offset:14336
	global_load_dwordx4 v[94:97], v210, s[68:69]
	s_waitcnt vmcnt(8)
	ds_write_b128 v202, v[174:177]
	ds_read_b128 v[170:173], v228 offset:36864
	s_waitcnt lgkmcnt(10)
	v_mfma_f32_16x16x32_bf16 v[74:77], v[238:241], v[212:215], v[74:77]
	v_mfma_f32_16x16x32_bf16 v[78:81], v[238:241], v[216:219], v[78:81]
	v_mfma_f32_16x16x32_bf16 v[82:85], v[238:241], v[220:223], v[82:85]
	v_mfma_f32_16x16x32_bf16 v[114:117], v[238:241], v[234:237], v[114:117]
	ds_read_b128 v[238:241], v229
	global_load_dwordx4 v[98:101], v196, s[66:67]
	s_waitcnt vmcnt(8)
	ds_write_b128 v203, v[178:181]
	ds_read_b128 v[174:177], v228 offset:38912
	s_waitcnt lgkmcnt(11)
	v_mfma_f32_16x16x32_bf16 v[118:121], v[242:245], v[212:215], v[118:121]
	v_mfma_f32_16x16x32_bf16 v[122:125], v[242:245], v[216:219], v[122:125]
	v_mfma_f32_16x16x32_bf16 v[126:129], v[242:245], v[220:223], v[126:129]
	v_mfma_f32_16x16x32_bf16 v[130:133], v[242:245], v[234:237], v[130:133]
	ds_read_b128 v[242:245], v229 offset:2048
	global_load_dwordx4 v[102:105], v208, s[66:67]
	s_waitcnt vmcnt(8)
	ds_write_b128 v204, v[182:185]
	s_waitcnt lgkmcnt(10)
	v_mfma_f32_16x16x32_bf16 v[134:137], v[246:249], v[212:215], v[134:137]
	v_mfma_f32_16x16x32_bf16 v[138:141], v[246:249], v[216:219], v[138:141]
	v_mfma_f32_16x16x32_bf16 v[142:145], v[246:249], v[220:223], v[142:145]
	v_mfma_f32_16x16x32_bf16 v[146:149], v[246:249], v[234:237], v[146:149]
	ds_read_b128 v[246:249], v229 offset:4096
	global_load_dwordx4 v[106:109], v209, s[66:67]
	s_waitcnt vmcnt(8)
	ds_write_b128 v205, v[186:189]
	s_waitcnt lgkmcnt(9)
	v_mfma_f32_16x16x32_bf16 v[150:153], v[250:253], v[212:215], v[150:153]
	v_mfma_f32_16x16x32_bf16 v[154:157], v[250:253], v[216:219], v[154:157]
	v_mfma_f32_16x16x32_bf16 v[158:161], v[250:253], v[220:223], v[158:161]
	v_mfma_f32_16x16x32_bf16 v[2:5], v[250:253], v[234:237], v[2:5]
	ds_read_b128 v[250:253], v229 offset:6144
	global_load_dwordx4 v[110:113], v210, s[66:67]
	s_waitcnt vmcnt(8)
	ds_write_b128 v206, v[190:193]
	s_waitcnt lgkmcnt(6)
	v_mfma_f32_16x16x32_bf16 v[6:9], v[238:241], v[162:165], v[6:9]
	v_mfma_f32_16x16x32_bf16 v[10:13], v[238:241], v[166:169], v[10:13]
	v_mfma_f32_16x16x32_bf16 v[14:17], v[238:241], v[170:173], v[14:17]
	v_mfma_f32_16x16x32_bf16 v[22:25], v[238:241], v[174:177], v[22:25]
	ds_read_b128 v[238:241], v229 offset:8192
	s_waitcnt lgkmcnt(6)
	v_mfma_f32_16x16x32_bf16 v[26:29], v[242:245], v[162:165], v[26:29]
	v_mfma_f32_16x16x32_bf16 v[30:33], v[242:245], v[166:169], v[30:33]
	v_mfma_f32_16x16x32_bf16 v[34:37], v[242:245], v[170:173], v[34:37]
	v_mfma_f32_16x16x32_bf16 v[38:41], v[242:245], v[174:177], v[38:41]
	ds_read_b128 v[242:245], v229 offset:10240
	s_waitcnt lgkmcnt(5)
	v_mfma_f32_16x16x32_bf16 v[42:45], v[246:249], v[162:165], v[42:45]
	v_mfma_f32_16x16x32_bf16 v[46:49], v[246:249], v[166:169], v[46:49]
	v_mfma_f32_16x16x32_bf16 v[50:53], v[246:249], v[170:173], v[50:53]
	v_mfma_f32_16x16x32_bf16 v[54:57], v[246:249], v[174:177], v[54:57]
	ds_read_b128 v[246:249], v229 offset:12288
	s_waitcnt lgkmcnt(4)
	v_mfma_f32_16x16x32_bf16 v[58:61], v[250:253], v[162:165], v[58:61]
	v_mfma_f32_16x16x32_bf16 v[62:65], v[250:253], v[166:169], v[62:65]
	v_mfma_f32_16x16x32_bf16 v[66:69], v[250:253], v[170:173], v[66:69]
	v_mfma_f32_16x16x32_bf16 v[70:73], v[250:253], v[174:177], v[70:73]
	ds_read_b128 v[250:253], v229 offset:14336
	s_waitcnt lgkmcnt(3)
	v_mfma_f32_16x16x32_bf16 v[74:77], v[238:241], v[162:165], v[74:77]
	v_mfma_f32_16x16x32_bf16 v[78:81], v[238:241], v[166:169], v[78:81]
	v_mfma_f32_16x16x32_bf16 v[82:85], v[238:241], v[170:173], v[82:85]
	v_mfma_f32_16x16x32_bf16 v[114:117], v[238:241], v[174:177], v[114:117]
	s_waitcnt lgkmcnt(2)
	v_mfma_f32_16x16x32_bf16 v[118:121], v[242:245], v[162:165], v[118:121]
	v_mfma_f32_16x16x32_bf16 v[122:125], v[242:245], v[166:169], v[122:125]
	v_mfma_f32_16x16x32_bf16 v[126:129], v[242:245], v[170:173], v[126:129]
	v_mfma_f32_16x16x32_bf16 v[130:133], v[242:245], v[174:177], v[130:133]
	s_waitcnt lgkmcnt(0)
	s_addk_i32 s62, 0x80
	s_add_u32 s54, s54, 0x100
	s_addc_u32 s55, s55, 0
	s_add_u32 s52, s52, 0x100
	s_addc_u32 s53, s53, 0
	s_cmp_gt_u32 s64, 12
	s_mov_b32 s64, s63
	s_cbranch_scc1 .Lgemm_out_exit
	s_barrier
	ds_read_b128 v[212:215], v230
	ds_read_b128 v[216:219], v230 offset:2048
	ds_read_b128 v[220:223], v230 offset:4096
	ds_read_b128 v[234:237], v230 offset:6144
	ds_read_b128 v[238:241], v231
	ds_read_b128 v[242:245], v231 offset:2048
	v_mfma_f32_16x16x32_bf16 v[134:137], v[246:249], v[162:165], v[134:137]
	v_mfma_f32_16x16x32_bf16 v[138:141], v[246:249], v[166:169], v[138:141]
	v_mfma_f32_16x16x32_bf16 v[142:145], v[246:249], v[170:173], v[142:145]
	v_mfma_f32_16x16x32_bf16 v[146:149], v[246:249], v[174:177], v[146:149]
	ds_read_b128 v[246:249], v231 offset:4096
	v_mfma_f32_16x16x32_bf16 v[150:153], v[250:253], v[162:165], v[150:153]
	v_mfma_f32_16x16x32_bf16 v[154:157], v[250:253], v[166:169], v[154:157]
	v_mfma_f32_16x16x32_bf16 v[158:161], v[250:253], v[170:173], v[158:161]
	v_mfma_f32_16x16x32_bf16 v[2:5], v[250:253], v[174:177], v[2:5]
	ds_read_b128 v[250:253], v231 offset:6144
	s_branch .LBB0_70

; template <int EPI>
; DI void gemm_phase(const P& p, int l, const u16* __restrict__ A, const u16* __restrict__ Bt, int mpx, char* lds) {
;     ...
;   {
;   const int lane = tid & 63, w = tid >> 6, r = lane & 15, g = lane >> 4, wm = w >> 2, wn = w & 3;
;   __syncthreads();
;   GLOAD(Ag, Bg, 64)
;   __builtin_amdgcn_sched_barrier(0);
;   GCOMPUTE_KS(As0, Bs0, 0)
;   __builtin_amdgcn_sched_barrier(0);
;   GSTORE(As1, Bs1)
;   GLOAD(Ag, Bg, 128)
;   __builtin_amdgcn_sched_barrier(0);
;   GCOMPUTE_KS(As0, Bs0, 1)
.LBB0_81:
	v_lshl_add_u64 v[138:139], s[40:41], 0, v[196:197]
	v_add_co_u32_e32 v140, vcc, s33, v138
	v_lshl_add_u64 v[146:147], s[0:1], 0, v[196:197]
	s_nop 0
	v_addc_co_u32_e32 v141, vcc, 0, v139, vcc
	v_add_co_u32_e32 v142, vcc, s35, v138
	s_waitcnt lgkmcnt(0)
	s_nop 0
	v_addc_co_u32_e32 v143, vcc, 0, v139, vcc
	v_add_co_u32_e32 v144, vcc, s39, v138
	s_barrier
	s_nop 0
	v_addc_co_u32_e32 v145, vcc, 0, v139, vcc
	v_add_co_u32_e32 v150, vcc, s33, v146
	s_nop 1
	v_addc_co_u32_e32 v151, vcc, 0, v147, vcc
	v_add_co_u32_e32 v154, vcc, s35, v146
	global_load_dwordx4 v[2:5], v[138:139], off offset:128
	global_load_dwordx4 v[6:9], v[140:141], off offset:128
	v_addc_co_u32_e32 v155, vcc, 0, v147, vcc
	v_add_co_u32_e32 v158, vcc, s39, v146
	global_load_dwordx4 v[10:13], v[142:143], off offset:128
	global_load_dwordx4 v[14:17], v[144:145], off offset:128
	global_load_dwordx4 v[18:21], v[146:147], off offset:128
	global_load_dwordx4 v[22:25], v[150:151], off offset:128
	v_addc_co_u32_e32 v159, vcc, 0, v147, vcc
	global_load_dwordx4 v[26:29], v[154:155], off offset:128
	global_load_dwordx4 v[30:33], v[158:159], off offset:128
	s_mov_b32 s57, s3
	s_lshl_b64 s[42:43], s[56:57], 11
	s_lshl_b32 s2, s51, 11
	s_add_u32 s58, s16, s42
	s_addc_u32 s59, s17, s43
	ds_read_b128 v[34:37], v205
	ds_read_b128 v[38:41], v204 offset:32768
	ds_read_b128 v[42:45], v204 offset:34816
	ds_read_b128 v[46:49], v205 offset:2048
	ds_read_b128 v[58:61], v204 offset:36864
	ds_read_b128 v[62:65], v204 offset:38912
	ds_read_b128 v[82:85], v205 offset:4096
	ds_read_b128 v[86:89], v205 offset:6144
	ds_read_b128 v[114:117], v205 offset:8192
	ds_read_b128 v[118:121], v205 offset:10240
	s_waitcnt vmcnt(25)
	ds_read_b128 v[130:133], v205 offset:12288
	s_waitcnt vmcnt(24)
	ds_read_b128 v[134:137], v205 offset:14336
	s_waitcnt lgkmcnt(10)
	v_mfma_f32_16x16x32_bf16 v[50:53], v[34:37], v[38:41], 0
	s_add_u32 s60, s24, s2
	s_addc_u32 s61, s25, 0
	s_waitcnt lgkmcnt(9)
	v_mfma_f32_16x16x32_bf16 v[54:57], v[34:37], v[42:45], 0
	s_waitcnt lgkmcnt(7)
	v_mfma_f32_16x16x32_bf16 v[66:69], v[34:37], v[58:61], 0
	s_waitcnt lgkmcnt(6)
	v_mfma_f32_16x16x32_bf16 v[34:37], v[34:37], v[62:65], 0
	v_mfma_f32_16x16x32_bf16 v[70:73], v[46:49], v[38:41], 0
	v_mfma_f32_16x16x32_bf16 v[74:77], v[46:49], v[42:45], 0
	v_mfma_f32_16x16x32_bf16 v[78:81], v[46:49], v[58:61], 0
	v_mfma_f32_16x16x32_bf16 v[46:49], v[46:49], v[62:65], 0
	s_waitcnt lgkmcnt(5)
	v_mfma_f32_16x16x32_bf16 v[90:93], v[82:85], v[38:41], 0
	v_mfma_f32_16x16x32_bf16 v[94:97], v[82:85], v[42:45], 0
	v_mfma_f32_16x16x32_bf16 v[98:101], v[82:85], v[58:61], 0
	v_mfma_f32_16x16x32_bf16 v[82:85], v[82:85], v[62:65], 0
	s_waitcnt lgkmcnt(4)
	v_mfma_f32_16x16x32_bf16 v[102:105], v[86:89], v[38:41], 0
	v_mfma_f32_16x16x32_bf16 v[106:109], v[86:89], v[42:45], 0
	v_mfma_f32_16x16x32_bf16 v[110:113], v[86:89], v[58:61], 0
	v_mfma_f32_16x16x32_bf16 v[86:89], v[86:89], v[62:65], 0
	s_waitcnt lgkmcnt(3)
	v_mfma_f32_16x16x32_bf16 v[122:125], v[114:117], v[38:41], 0
	v_mfma_f32_16x16x32_bf16 v[126:129], v[114:117], v[42:45], 0
	v_mfma_f32_16x16x32_bf16 v[162:165], v[114:117], v[58:61], 0
	v_mfma_f32_16x16x32_bf16 v[114:117], v[114:117], v[62:65], 0
	s_waitcnt lgkmcnt(2)
	v_mfma_f32_16x16x32_bf16 v[166:169], v[118:121], v[38:41], 0
	v_mfma_f32_16x16x32_bf16 v[170:173], v[118:121], v[42:45], 0
	v_mfma_f32_16x16x32_bf16 v[174:177], v[118:121], v[58:61], 0
	v_mfma_f32_16x16x32_bf16 v[118:121], v[118:121], v[62:65], 0
	s_waitcnt lgkmcnt(1)
	v_mfma_f32_16x16x32_bf16 v[178:181], v[130:133], v[38:41], 0
	v_mfma_f32_16x16x32_bf16 v[182:185], v[130:133], v[42:45], 0
	v_mfma_f32_16x16x32_bf16 v[186:189], v[130:133], v[58:61], 0
	v_mfma_f32_16x16x32_bf16 v[190:193], v[130:133], v[62:65], 0
	s_waitcnt lgkmcnt(0)
	v_mfma_f32_16x16x32_bf16 v[234:237], v[134:137], v[38:41], 0
	v_mfma_f32_16x16x32_bf16 v[238:241], v[134:137], v[42:45], 0
	v_mfma_f32_16x16x32_bf16 v[242:245], v[134:137], v[58:61], 0
	v_mfma_f32_16x16x32_bf16 v[246:249], v[134:137], v[62:65], 0
	s_waitcnt vmcnt(7)
	ds_write_b128 v202, v[2:5]
	s_waitcnt vmcnt(6)
	ds_write_b128 v227, v[6:9]
	s_waitcnt vmcnt(5)
	ds_write_b128 v228, v[10:13]
	s_waitcnt vmcnt(4)
	ds_write_b128 v229, v[14:17]
	s_waitcnt vmcnt(3)
	ds_write_b128 v203, v[18:21]
	s_waitcnt vmcnt(2)
	ds_write_b128 v230, v[22:25]
	s_waitcnt vmcnt(1)
	ds_write_b128 v231, v[26:29]
	s_waitcnt vmcnt(0)
	ds_write_b128 v232, v[30:33]
	global_load_dwordx4 v[130:133], v[138:139], off offset:256
	global_load_dwordx4 v[134:137], v[140:141], off offset:256
	s_nop 0
	global_load_dwordx4 v[138:141], v[142:143], off offset:256
	s_nop 0
	global_load_dwordx4 v[142:145], v[144:145], off offset:256
	s_nop 0
	global_load_dwordx4 v[146:149], v[146:147], off offset:256
	s_nop 0
	global_load_dwordx4 v[150:153], v[150:151], off offset:256
	s_nop 0
	global_load_dwordx4 v[154:157], v[154:155], off offset:256
	s_nop 0
	global_load_dwordx4 v[158:161], v[158:159], off offset:256
	ds_read_b128 v[2:5], v207
	ds_read_b128 v[250:253], v206 offset:32768
	ds_read_b128 v[216:219], v206 offset:34816
	ds_read_b128 v[212:215], v206 offset:36864
	ds_read_b128 v[220:223], v206 offset:38912
	s_waitcnt lgkmcnt(3)
	v_mfma_f32_16x16x32_bf16 v[6:9], v[2:5], v[250:253], v[50:53]
	s_waitcnt lgkmcnt(2)
	v_mfma_f32_16x16x32_bf16 v[10:13], v[2:5], v[216:219], v[54:57]
	s_waitcnt lgkmcnt(1)
	v_mfma_f32_16x16x32_bf16 v[14:17], v[2:5], v[212:215], v[66:69]
	s_waitcnt lgkmcnt(0)
	v_mfma_f32_16x16x32_bf16 v[18:21], v[2:5], v[220:223], v[34:37]
	ds_read_b128 v[2:5], v207 offset:2048
	s_waitcnt lgkmcnt(0)
; #define GCOMPUTE(AS, BS) GCOMPUTE_KS(AS, BS, 0) GCOMPUTE_KS(AS, BS, 1)
; template <int EPI>
; DI void gemm_phase(const P& p, int l, const u16* __restrict__ A, const u16* __restrict__ Bt, int mpx, char* lds) {
;     ...
;   GCOMPUTE_KS(As0, Bs0, 1)
;   __builtin_amdgcn_sched_barrier(0);
; #pragma unroll 1
;   for (int kk = 1; kk < 15; kk += 2) {
;     __syncthreads();
;     GSTORE(As0, Bs0)
;     GLOAD(Ag, Bg, (kk + 2) * 64)
;     __builtin_amdgcn_sched_barrier(0);
;     GCOMPUTE(As1, Bs1)
;     __builtin_amdgcn_sched_barrier(0);
;     __syncthreads();
;     GSTORE(As1, Bs1)
	v_mfma_f32_16x16x32_bf16 v[22:25], v[2:5], v[250:253], v[70:73]
	v_mfma_f32_16x16x32_bf16 v[26:29], v[2:5], v[216:219], v[74:77]
	v_mfma_f32_16x16x32_bf16 v[30:33], v[2:5], v[212:215], v[78:81]
	v_mfma_f32_16x16x32_bf16 v[34:37], v[2:5], v[220:223], v[46:49]
	ds_read_b128 v[2:5], v207 offset:4096
	s_waitcnt lgkmcnt(0)
	v_mfma_f32_16x16x32_bf16 v[38:41], v[2:5], v[250:253], v[90:93]
	v_mfma_f32_16x16x32_bf16 v[42:45], v[2:5], v[216:219], v[94:97]
	v_mfma_f32_16x16x32_bf16 v[46:49], v[2:5], v[212:215], v[98:101]
	v_mfma_f32_16x16x32_bf16 v[50:53], v[2:5], v[220:223], v[82:85]
	ds_read_b128 v[2:5], v207 offset:6144
	s_waitcnt lgkmcnt(0)
	v_mfma_f32_16x16x32_bf16 v[54:57], v[2:5], v[250:253], v[102:105]
	v_mfma_f32_16x16x32_bf16 v[58:61], v[2:5], v[216:219], v[106:109]
	v_mfma_f32_16x16x32_bf16 v[62:65], v[2:5], v[212:215], v[110:113]
	v_mfma_f32_16x16x32_bf16 v[66:69], v[2:5], v[220:223], v[86:89]
	ds_read_b128 v[2:5], v207 offset:8192
	s_waitcnt lgkmcnt(0)
	v_mfma_f32_16x16x32_bf16 v[70:73], v[2:5], v[250:253], v[122:125]
	v_mfma_f32_16x16x32_bf16 v[74:77], v[2:5], v[216:219], v[126:129]
	v_mfma_f32_16x16x32_bf16 v[78:81], v[2:5], v[212:215], v[162:165]
	v_mfma_f32_16x16x32_bf16 v[82:85], v[2:5], v[220:223], v[114:117]
	ds_read_b128 v[2:5], v207 offset:10240
	s_waitcnt lgkmcnt(0)
	v_mfma_f32_16x16x32_bf16 v[86:89], v[2:5], v[250:253], v[166:169]
	v_mfma_f32_16x16x32_bf16 v[90:93], v[2:5], v[216:219], v[170:173]
	v_mfma_f32_16x16x32_bf16 v[94:97], v[2:5], v[212:215], v[174:177]
	v_mfma_f32_16x16x32_bf16 v[98:101], v[2:5], v[220:223], v[118:121]
	ds_read_b128 v[2:5], v207 offset:12288
	s_waitcnt lgkmcnt(0)
	v_mfma_f32_16x16x32_bf16 v[102:105], v[2:5], v[250:253], v[178:181]
	v_mfma_f32_16x16x32_bf16 v[106:109], v[2:5], v[216:219], v[182:185]
	v_mfma_f32_16x16x32_bf16 v[110:113], v[2:5], v[212:215], v[186:189]
	v_mfma_f32_16x16x32_bf16 v[114:117], v[2:5], v[220:223], v[190:193]
	ds_read_b128 v[2:5], v207 offset:14336
	s_waitcnt lgkmcnt(0)
	v_mfma_f32_16x16x32_bf16 v[118:121], v[2:5], v[250:253], v[234:237]
	v_mfma_f32_16x16x32_bf16 v[122:125], v[2:5], v[216:219], v[238:241]
	v_mfma_f32_16x16x32_bf16 v[126:129], v[2:5], v[212:215], v[242:245]
	v_mfma_f32_16x16x32_bf16 v[2:5], v[2:5], v[220:223], v[246:249]
	s_mov_b32 s49, 1
	s_movk_i32 s47, 0x100
	s_mov_b64 s[42:43], s[0:1]
	s_mov_b64 s[44:45], s[40:41]
	v_add_u32_e32 v208, s33, v196
	v_add_u32_e32 v209, s35, v196
	v_add_u32_e32 v210, s39, v196
	s_barrier
	ds_read_b128 v[212:215], v198
	ds_read_b128 v[216:219], v198 offset:2048
	ds_read_b128 v[220:223], v198 offset:4096
	ds_read_b128 v[234:237], v198 offset:6144
	ds_read_b128 v[238:241], v199
	ds_read_b128 v[242:245], v199 offset:2048
	ds_read_b128 v[246:249], v199 offset:4096
	ds_read_b128 v[250:253], v199 offset:6144
.LBB0_82:
	s_add_i32 s48, s49, 2
	s_waitcnt lgkmcnt(3)
	v_mfma_f32_16x16x32_bf16 v[6:9], v[238:241], v[212:215], v[6:9]
	v_mfma_f32_16x16x32_bf16 v[10:13], v[238:241], v[216:219], v[10:13]
	v_mfma_f32_16x16x32_bf16 v[14:17], v[238:241], v[220:223], v[14:17]
	v_mfma_f32_16x16x32_bf16 v[18:21], v[238:241], v[234:237], v[18:21]
	ds_read_b128 v[238:241], v199 offset:8192
	global_load_dwordx4 v[162:165], v196, s[44:45] offset:384
	s_waitcnt vmcnt(8)
	ds_write_b128 v201, v[130:133]
	s_waitcnt lgkmcnt(4)
	v_mfma_f32_16x16x32_bf16 v[22:25], v[242:245], v[212:215], v[22:25]
	v_mfma_f32_16x16x32_bf16 v[26:29], v[242:245], v[216:219], v[26:29]
	v_mfma_f32_16x16x32_bf16 v[30:33], v[242:245], v[220:223], v[30:33]
	v_mfma_f32_16x16x32_bf16 v[34:37], v[242:245], v[234:237], v[34:37]
	ds_read_b128 v[242:245], v199 offset:10240
	global_load_dwordx4 v[166:169], v208, s[44:45] offset:384
	s_waitcnt vmcnt(8)
	ds_write_b128 v201, v[134:137] offset:8192
	ds_read_b128 v[130:133], v200
	s_waitcnt lgkmcnt(6)
	v_mfma_f32_16x16x32_bf16 v[38:41], v[246:249], v[212:215], v[38:41]
	v_mfma_f32_16x16x32_bf16 v[42:45], v[246:249], v[216:219], v[42:45]
	v_mfma_f32_16x16x32_bf16 v[46:49], v[246:249], v[220:223], v[46:49]
	v_mfma_f32_16x16x32_bf16 v[50:53], v[246:249], v[234:237], v[50:53]
	ds_read_b128 v[246:249], v199 offset:12288
	global_load_dwordx4 v[170:173], v209, s[44:45] offset:384
	s_waitcnt vmcnt(8)
	ds_write_b128 v201, v[138:141] offset:16384
	ds_read_b128 v[134:137], v200 offset:2048
	s_waitcnt lgkmcnt(8)
	v_mfma_f32_16x16x32_bf16 v[54:57], v[250:253], v[212:215], v[54:57]
	v_mfma_f32_16x16x32_bf16 v[58:61], v[250:253], v[216:219], v[58:61]
	v_mfma_f32_16x16x32_bf16 v[62:65], v[250:253], v[220:223], v[62:65]
	v_mfma_f32_16x16x32_bf16 v[66:69], v[250:253], v[234:237], v[66:69]
	ds_read_b128 v[250:253], v199 offset:14336
	global_load_dwordx4 v[174:177], v210, s[44:45] offset:384
	s_waitcnt vmcnt(8)
	ds_write_b128 v201, v[142:145] offset:24576
	ds_read_b128 v[138:141], v200 offset:4096
	s_waitcnt lgkmcnt(10)
	v_mfma_f32_16x16x32_bf16 v[70:73], v[238:241], v[212:215], v[70:73]
	v_mfma_f32_16x16x32_bf16 v[74:77], v[238:241], v[216:219], v[74:77]
	v_mfma_f32_16x16x32_bf16 v[78:81], v[238:241], v[220:223], v[78:81]
	v_mfma_f32_16x16x32_bf16 v[82:85], v[238:241], v[234:237], v[82:85]
	ds_read_b128 v[238:241], v233
	global_load_dwordx4 v[178:181], v196, s[42:43] offset:384
	s_waitcnt vmcnt(8)
	ds_write_b128 v201, v[146:149] offset:32768
	ds_read_b128 v[142:145], v200 offset:6144
	s_waitcnt lgkmcnt(11)
	v_mfma_f32_16x16x32_bf16 v[86:89], v[242:245], v[212:215], v[86:89]
	v_mfma_f32_16x16x32_bf16 v[90:93], v[242:245], v[216:219], v[90:93]
	v_mfma_f32_16x16x32_bf16 v[94:97], v[242:245], v[220:223], v[94:97]
	v_mfma_f32_16x16x32_bf16 v[98:101], v[242:245], v[234:237], v[98:101]
	ds_read_b128 v[242:245], v233 offset:2048
	global_load_dwordx4 v[182:185], v208, s[42:43] offset:384
	s_waitcnt vmcnt(8)
; #define GCOMPUTE(AS, BS) GCOMPUTE_KS(AS, BS, 0) GCOMPUTE_KS(AS, BS, 1)
; template <int EPI>
; DI void gemm_phase(const P& p, int l, const u16* __restrict__ A, const u16* __restrict__ Bt, int mpx, char* lds) {
;     ...
;     __syncthreads();
;     GSTORE(As1, Bs1)
;     {
;       const bool in_tile = kk + 3 < 16;
;       const u16* pa = in_tile ? Ag : Agn;
;       const u16* pb = in_tile ? Bg : Bgn;
;       const int k0 = in_tile ? (kk + 3) * 64 : 0;
;       GLOAD(pa, pb, k0)
;     }
;     __builtin_amdgcn_sched_barrier(0);
;     GCOMPUTE(As0, Bs0)
	ds_write_b128 v201, v[150:153] offset:40960
	s_waitcnt lgkmcnt(10)
	v_mfma_f32_16x16x32_bf16 v[102:105], v[246:249], v[212:215], v[102:105]
	v_mfma_f32_16x16x32_bf16 v[106:109], v[246:249], v[216:219], v[106:109]
	v_mfma_f32_16x16x32_bf16 v[110:113], v[246:249], v[220:223], v[110:113]
	v_mfma_f32_16x16x32_bf16 v[114:117], v[246:249], v[234:237], v[114:117]
	ds_read_b128 v[246:249], v233 offset:4096
	global_load_dwordx4 v[186:189], v209, s[42:43] offset:384
	s_waitcnt vmcnt(8)
	ds_write_b128 v201, v[154:157] offset:49152
	s_waitcnt lgkmcnt(9)
	v_mfma_f32_16x16x32_bf16 v[118:121], v[250:253], v[212:215], v[118:121]
	v_mfma_f32_16x16x32_bf16 v[122:125], v[250:253], v[216:219], v[122:125]
	v_mfma_f32_16x16x32_bf16 v[126:129], v[250:253], v[220:223], v[126:129]
	v_mfma_f32_16x16x32_bf16 v[2:5], v[250:253], v[234:237], v[2:5]
	ds_read_b128 v[250:253], v233 offset:6144
	global_load_dwordx4 v[190:193], v210, s[42:43] offset:384
	s_waitcnt vmcnt(8)
	ds_write_b128 v201, v[158:161] offset:57344
	s_waitcnt lgkmcnt(6)
	v_mfma_f32_16x16x32_bf16 v[6:9], v[238:241], v[130:133], v[6:9]
	v_mfma_f32_16x16x32_bf16 v[10:13], v[238:241], v[134:137], v[10:13]
	v_mfma_f32_16x16x32_bf16 v[14:17], v[238:241], v[138:141], v[14:17]
	v_mfma_f32_16x16x32_bf16 v[18:21], v[238:241], v[142:145], v[18:21]
	ds_read_b128 v[238:241], v233 offset:8192
	s_waitcnt lgkmcnt(6)
	v_mfma_f32_16x16x32_bf16 v[22:25], v[242:245], v[130:133], v[22:25]
	v_mfma_f32_16x16x32_bf16 v[26:29], v[242:245], v[134:137], v[26:29]
	v_mfma_f32_16x16x32_bf16 v[30:33], v[242:245], v[138:141], v[30:33]
	v_mfma_f32_16x16x32_bf16 v[34:37], v[242:245], v[142:145], v[34:37]
	ds_read_b128 v[242:245], v233 offset:10240
	s_waitcnt lgkmcnt(5)
	v_mfma_f32_16x16x32_bf16 v[38:41], v[246:249], v[130:133], v[38:41]
	v_mfma_f32_16x16x32_bf16 v[42:45], v[246:249], v[134:137], v[42:45]
	v_mfma_f32_16x16x32_bf16 v[46:49], v[246:249], v[138:141], v[46:49]
	v_mfma_f32_16x16x32_bf16 v[50:53], v[246:249], v[142:145], v[50:53]
	ds_read_b128 v[246:249], v233 offset:12288
	s_waitcnt lgkmcnt(4)
	v_mfma_f32_16x16x32_bf16 v[54:57], v[250:253], v[130:133], v[54:57]
	v_mfma_f32_16x16x32_bf16 v[58:61], v[250:253], v[134:137], v[58:61]
	v_mfma_f32_16x16x32_bf16 v[62:65], v[250:253], v[138:141], v[62:65]
	v_mfma_f32_16x16x32_bf16 v[66:69], v[250:253], v[142:145], v[66:69]
	ds_read_b128 v[250:253], v233 offset:14336
	s_waitcnt lgkmcnt(3)
	v_mfma_f32_16x16x32_bf16 v[70:73], v[238:241], v[130:133], v[70:73]
	v_mfma_f32_16x16x32_bf16 v[74:77], v[238:241], v[134:137], v[74:77]
	v_mfma_f32_16x16x32_bf16 v[78:81], v[238:241], v[138:141], v[78:81]
	v_mfma_f32_16x16x32_bf16 v[82:85], v[238:241], v[142:145], v[82:85]
	s_waitcnt lgkmcnt(2)
	v_mfma_f32_16x16x32_bf16 v[86:89], v[242:245], v[130:133], v[86:89]
	v_mfma_f32_16x16x32_bf16 v[90:93], v[242:245], v[134:137], v[90:93]
	v_mfma_f32_16x16x32_bf16 v[94:97], v[242:245], v[138:141], v[94:97]
	v_mfma_f32_16x16x32_bf16 v[98:101], v[242:245], v[142:145], v[98:101]
	s_waitcnt lgkmcnt(0)
	s_cmp_lt_u32 s49, 13
	s_cselect_b64 s[62:63], -1, 0
	s_and_b64 s[62:63], s[62:63], exec
	s_cselect_b32 s2, s47, 0
	s_cselect_b32 s57, s41, s59
	s_cselect_b32 s64, s40, s58
	s_cselect_b32 s67, s1, s61
	s_cselect_b32 s68, s0, s60
	s_lshl_b64 s[62:63], s[2:3], 1
	s_add_u32 s64, s64, s62
	s_addc_u32 s65, s57, s63
	s_add_u32 s62, s68, s62
	s_addc_u32 s63, s67, s63
	s_barrier
	ds_read_b128 v[212:215], v204 offset:32768
	ds_read_b128 v[216:219], v204 offset:34816
	ds_read_b128 v[220:223], v204 offset:36864
	ds_read_b128 v[234:237], v204 offset:38912
	ds_read_b128 v[238:241], v205
	ds_read_b128 v[242:245], v205 offset:2048
	v_mfma_f32_16x16x32_bf16 v[102:105], v[246:249], v[130:133], v[102:105]
	v_mfma_f32_16x16x32_bf16 v[106:109], v[246:249], v[134:137], v[106:109]
	v_mfma_f32_16x16x32_bf16 v[110:113], v[246:249], v[138:141], v[110:113]
	v_mfma_f32_16x16x32_bf16 v[114:117], v[246:249], v[142:145], v[114:117]
	ds_read_b128 v[246:249], v205 offset:4096
	v_mfma_f32_16x16x32_bf16 v[118:121], v[250:253], v[130:133], v[118:121]
	v_mfma_f32_16x16x32_bf16 v[122:125], v[250:253], v[134:137], v[122:125]
	v_mfma_f32_16x16x32_bf16 v[126:129], v[250:253], v[138:141], v[126:129]
	v_mfma_f32_16x16x32_bf16 v[2:5], v[250:253], v[142:145], v[2:5]
	ds_read_b128 v[250:253], v205 offset:6144
	s_waitcnt lgkmcnt(3)
	v_mfma_f32_16x16x32_bf16 v[6:9], v[238:241], v[212:215], v[6:9]
	v_mfma_f32_16x16x32_bf16 v[10:13], v[238:241], v[216:219], v[10:13]
	v_mfma_f32_16x16x32_bf16 v[14:17], v[238:241], v[220:223], v[14:17]
	v_mfma_f32_16x16x32_bf16 v[18:21], v[238:241], v[234:237], v[18:21]
	ds_read_b128 v[238:241], v205 offset:8192
	global_load_dwordx4 v[130:133], v196, s[64:65]
	s_waitcnt vmcnt(8)
	ds_write_b128 v202, v[162:165]
	s_waitcnt lgkmcnt(4)
	v_mfma_f32_16x16x32_bf16 v[22:25], v[242:245], v[212:215], v[22:25]
	v_mfma_f32_16x16x32_bf16 v[26:29], v[242:245], v[216:219], v[26:29]
	v_mfma_f32_16x16x32_bf16 v[30:33], v[242:245], v[220:223], v[30:33]
	v_mfma_f32_16x16x32_bf16 v[34:37], v[242:245], v[234:237], v[34:37]
	ds_read_b128 v[242:245], v205 offset:10240
	global_load_dwordx4 v[134:137], v208, s[64:65]
	s_waitcnt vmcnt(8)
	ds_write_b128 v227, v[166:169]
	ds_read_b128 v[162:165], v206 offset:32768
	s_waitcnt lgkmcnt(6)
	v_mfma_f32_16x16x32_bf16 v[38:41], v[246:249], v[212:215], v[38:41]
	v_mfma_f32_16x16x32_bf16 v[42:45], v[246:249], v[216:219], v[42:45]
	v_mfma_f32_16x16x32_bf16 v[46:49], v[246:249], v[220:223], v[46:49]
	v_mfma_f32_16x16x32_bf16 v[50:53], v[246:249], v[234:237], v[50:53]
	ds_read_b128 v[246:249], v205 offset:12288
	global_load_dwordx4 v[138:141], v209, s[64:65]
	s_waitcnt vmcnt(8)
; #define GCOMPUTE(AS, BS) GCOMPUTE_KS(AS, BS, 0) GCOMPUTE_KS(AS, BS, 1)
; template <int EPI>
; DI void gemm_phase(const P& p, int l, const u16* __restrict__ A, const u16* __restrict__ Bt, int mpx, char* lds) {
;     ...
;   for (int kk = 1; kk < 15; kk += 2) {
;     __syncthreads();
;     GSTORE(As0, Bs0)
;     GLOAD(Ag, Bg, (kk + 2) * 64)
;     __builtin_amdgcn_sched_barrier(0);
;     GCOMPUTE(As1, Bs1)
;     __builtin_amdgcn_sched_barrier(0);
;     __syncthreads();
;     GSTORE(As1, Bs1)
;     {
;       const bool in_tile = kk + 3 < 16;
;       const u16* pa = in_tile ? Ag : Agn;
;       const u16* pb = in_tile ? Bg : Bgn;
;       const int k0 = in_tile ? (kk + 3) * 64 : 0;
;       GLOAD(pa, pb, k0)
;     }
;     __builtin_amdgcn_sched_barrier(0);
;     GCOMPUTE(As0, Bs0)
;     __builtin_amdgcn_sched_barrier(0);
;   }
	ds_write_b128 v228, v[170:173]
	ds_read_b128 v[166:169], v206 offset:34816
	s_waitcnt lgkmcnt(8)
	v_mfma_f32_16x16x32_bf16 v[54:57], v[250:253], v[212:215], v[54:57]
	v_mfma_f32_16x16x32_bf16 v[58:61], v[250:253], v[216:219], v[58:61]
	v_mfma_f32_16x16x32_bf16 v[62:65], v[250:253], v[220:223], v[62:65]
	v_mfma_f32_16x16x32_bf16 v[66:69], v[250:253], v[234:237], v[66:69]
	ds_read_b128 v[250:253], v205 offset:14336
	global_load_dwordx4 v[142:145], v210, s[64:65]
	s_waitcnt vmcnt(8)
	ds_write_b128 v229, v[174:177]
	ds_read_b128 v[170:173], v206 offset:36864
	s_waitcnt lgkmcnt(10)
	v_mfma_f32_16x16x32_bf16 v[70:73], v[238:241], v[212:215], v[70:73]
	v_mfma_f32_16x16x32_bf16 v[74:77], v[238:241], v[216:219], v[74:77]
	v_mfma_f32_16x16x32_bf16 v[78:81], v[238:241], v[220:223], v[78:81]
	v_mfma_f32_16x16x32_bf16 v[82:85], v[238:241], v[234:237], v[82:85]
	ds_read_b128 v[238:241], v207
	global_load_dwordx4 v[146:149], v196, s[62:63]
	s_waitcnt vmcnt(8)
	ds_write_b128 v203, v[178:181]
	ds_read_b128 v[174:177], v206 offset:38912
	s_waitcnt lgkmcnt(11)
	v_mfma_f32_16x16x32_bf16 v[86:89], v[242:245], v[212:215], v[86:89]
	v_mfma_f32_16x16x32_bf16 v[90:93], v[242:245], v[216:219], v[90:93]
	v_mfma_f32_16x16x32_bf16 v[94:97], v[242:245], v[220:223], v[94:97]
	v_mfma_f32_16x16x32_bf16 v[98:101], v[242:245], v[234:237], v[98:101]
	ds_read_b128 v[242:245], v207 offset:2048
	global_load_dwordx4 v[150:153], v208, s[62:63]
	s_waitcnt vmcnt(8)
	ds_write_b128 v230, v[182:185]
	s_waitcnt lgkmcnt(10)
	v_mfma_f32_16x16x32_bf16 v[102:105], v[246:249], v[212:215], v[102:105]
	v_mfma_f32_16x16x32_bf16 v[106:109], v[246:249], v[216:219], v[106:109]
	v_mfma_f32_16x16x32_bf16 v[110:113], v[246:249], v[220:223], v[110:113]
	v_mfma_f32_16x16x32_bf16 v[114:117], v[246:249], v[234:237], v[114:117]
	ds_read_b128 v[246:249], v207 offset:4096
	global_load_dwordx4 v[154:157], v209, s[62:63]
	s_waitcnt vmcnt(8)
	ds_write_b128 v231, v[186:189]
	s_waitcnt lgkmcnt(9)
	v_mfma_f32_16x16x32_bf16 v[118:121], v[250:253], v[212:215], v[118:121]
	v_mfma_f32_16x16x32_bf16 v[122:125], v[250:253], v[216:219], v[122:125]
	v_mfma_f32_16x16x32_bf16 v[126:129], v[250:253], v[220:223], v[126:129]
	v_mfma_f32_16x16x32_bf16 v[2:5], v[250:253], v[234:237], v[2:5]
	ds_read_b128 v[250:253], v207 offset:6144
	global_load_dwordx4 v[158:161], v210, s[62:63]
	s_waitcnt vmcnt(8)
	ds_write_b128 v232, v[190:193]
	s_waitcnt lgkmcnt(6)
	v_mfma_f32_16x16x32_bf16 v[6:9], v[238:241], v[162:165], v[6:9]
	v_mfma_f32_16x16x32_bf16 v[10:13], v[238:241], v[166:169], v[10:13]
	v_mfma_f32_16x16x32_bf16 v[14:17], v[238:241], v[170:173], v[14:17]
	v_mfma_f32_16x16x32_bf16 v[18:21], v[238:241], v[174:177], v[18:21]
	ds_read_b128 v[238:241], v207 offset:8192
	s_waitcnt lgkmcnt(6)
	v_mfma_f32_16x16x32_bf16 v[22:25], v[242:245], v[162:165], v[22:25]
	v_mfma_f32_16x16x32_bf16 v[26:29], v[242:245], v[166:169], v[26:29]
	v_mfma_f32_16x16x32_bf16 v[30:33], v[242:245], v[170:173], v[30:33]
	v_mfma_f32_16x16x32_bf16 v[34:37], v[242:245], v[174:177], v[34:37]
	ds_read_b128 v[242:245], v207 offset:10240
	s_waitcnt lgkmcnt(5)
	v_mfma_f32_16x16x32_bf16 v[38:41], v[246:249], v[162:165], v[38:41]
	v_mfma_f32_16x16x32_bf16 v[42:45], v[246:249], v[166:169], v[42:45]
	v_mfma_f32_16x16x32_bf16 v[46:49], v[246:249], v[170:173], v[46:49]
	v_mfma_f32_16x16x32_bf16 v[50:53], v[246:249], v[174:177], v[50:53]
	ds_read_b128 v[246:249], v207 offset:12288
	s_waitcnt lgkmcnt(4)
	v_mfma_f32_16x16x32_bf16 v[54:57], v[250:253], v[162:165], v[54:57]
	v_mfma_f32_16x16x32_bf16 v[58:61], v[250:253], v[166:169], v[58:61]
	v_mfma_f32_16x16x32_bf16 v[62:65], v[250:253], v[170:173], v[62:65]
	v_mfma_f32_16x16x32_bf16 v[66:69], v[250:253], v[174:177], v[66:69]
	ds_read_b128 v[250:253], v207 offset:14336
	s_waitcnt lgkmcnt(3)
	v_mfma_f32_16x16x32_bf16 v[70:73], v[238:241], v[162:165], v[70:73]
	v_mfma_f32_16x16x32_bf16 v[74:77], v[238:241], v[166:169], v[74:77]
	v_mfma_f32_16x16x32_bf16 v[78:81], v[238:241], v[170:173], v[78:81]
	v_mfma_f32_16x16x32_bf16 v[82:85], v[238:241], v[174:177], v[82:85]
	s_waitcnt lgkmcnt(2)
	v_mfma_f32_16x16x32_bf16 v[86:89], v[242:245], v[162:165], v[86:89]
	v_mfma_f32_16x16x32_bf16 v[90:93], v[242:245], v[166:169], v[90:93]
	v_mfma_f32_16x16x32_bf16 v[94:97], v[242:245], v[170:173], v[94:97]
	v_mfma_f32_16x16x32_bf16 v[98:101], v[242:245], v[174:177], v[98:101]
	s_waitcnt lgkmcnt(0)
	s_addk_i32 s47, 0x80
	s_add_u32 s44, s44, 0x100
	s_addc_u32 s45, s45, 0
	s_add_u32 s42, s42, 0x100
	s_addc_u32 s43, s43, 0
	s_cmp_gt_u32 s49, 12
	s_mov_b32 s49, s48
	s_cbranch_scc1 .Lgemm_in_exit
	s_barrier
	ds_read_b128 v[212:215], v198
	ds_read_b128 v[216:219], v198 offset:2048
	ds_read_b128 v[220:223], v198 offset:4096
	ds_read_b128 v[234:237], v198 offset:6144
	ds_read_b128 v[238:241], v199
	ds_read_b128 v[242:245], v199 offset:2048
	v_mfma_f32_16x16x32_bf16 v[102:105], v[246:249], v[162:165], v[102:105]
	v_mfma_f32_16x16x32_bf16 v[106:109], v[246:249], v[166:169], v[106:109]
	v_mfma_f32_16x16x32_bf16 v[110:113], v[246:249], v[170:173], v[110:113]
	v_mfma_f32_16x16x32_bf16 v[114:117], v[246:249], v[174:177], v[114:117]
	ds_read_b128 v[246:249], v199 offset:4096
	v_mfma_f32_16x16x32_bf16 v[118:121], v[250:253], v[162:165], v[118:121]
	v_mfma_f32_16x16x32_bf16 v[122:125], v[250:253], v[166:169], v[122:125]
	v_mfma_f32_16x16x32_bf16 v[126:129], v[250:253], v[170:173], v[126:129]
	v_mfma_f32_16x16x32_bf16 v[2:5], v[250:253], v[174:177], v[2:5]
	ds_read_b128 v[250:253], v199 offset:6144
	s_branch .LBB0_82
